# v5: v3 + indexer threshold-search early exit + attention epilogues widened to dwordx4 loads/stores via permlane32_swap
# speedup vs baseline: 1.0460x; 1.0218x over previous
.LBB0_35:
	s_lshl_b64 s[0:1], s[26:27], 1
	s_add_u32 s2, s36, s0
	s_addc_u32 s9, s37, s1
	s_lshl_b32 s10, s41, 1
	s_add_u32 s8, s2, s10
	s_addc_u32 s9, s9, 0
	v_mov_b32_e32 v159, v1
	v_lshl_add_u64 v[66:67], s[8:9], 0, v[158:159]
	v_lshl_add_u64 v[66:67], v[66:67], 0, v[156:157]
	v_lshl_add_u64 v[66:67], v[66:67], 0, v[156:157]
	global_load_dwordx4 v[68:71], v[66:67], off
	global_load_dwordx4 v[72:75], v[66:67], off offset:32
	global_load_dwordx4 v[76:79], v[66:67], off offset:64
	global_load_dwordx4 v[80:83], v[66:67], off offset:96
	global_load_dwordx4 v[84:87], v[66:67], off offset:128
	global_load_dwordx4 v[88:91], v[66:67], off offset:160
	global_load_dwordx4 v[92:95], v[66:67], off offset:192
	global_load_dwordx4 v[96:99], v[66:67], off offset:224
	s_add_u32 s0, s39, s0
	s_addc_u32 s1, s40, s1
	s_add_u32 s0, s0, s10
	s_addc_u32 s1, s1, 0
	v_lshl_add_u64 v[106:107], s[0:1], 0, v[156:157]
	v_lshl_add_u64 v[106:107], v[106:107], 0, v[156:157]
	v_lshl_add_u64 v[106:107], v[106:107], 0, v[158:159]
	s_waitcnt vmcnt(7)
	v_permlane32_swap_b32_e32 v68, v70
	v_permlane32_swap_b32_e32 v69, v71
	v_lshlrev_b32_e32 v120, 16, v68
	v_and_b32_e32 v121, 0xffff0000, v68
	v_lshlrev_b32_e32 v122, 16, v69
	v_and_b32_e32 v123, 0xffff0000, v69
	v_mul_f32_e32 v116, v50, v120
	v_mul_f32_e32 v117, v51, v121
	v_mul_f32_e32 v118, v52, v122
	v_mul_f32_e32 v119, v53, v123
	v_cvt_pk_bf16_f32 v108, v116, v117
	v_cvt_pk_bf16_f32 v109, v118, v119
	v_lshlrev_b32_e32 v120, 16, v70
	v_and_b32_e32 v121, 0xffff0000, v70
	v_lshlrev_b32_e32 v122, 16, v71
	v_and_b32_e32 v123, 0xffff0000, v71
	v_mul_f32_e32 v116, v54, v120
	v_mul_f32_e32 v117, v55, v121
	v_mul_f32_e32 v118, v56, v122
	v_mul_f32_e32 v119, v57, v123
	v_cvt_pk_bf16_f32 v110, v116, v117
	v_cvt_pk_bf16_f32 v111, v118, v119
	s_nop 1
	v_permlane32_swap_b32_e32 v108, v110
	v_permlane32_swap_b32_e32 v109, v111
	global_store_dwordx4 v[106:107], v[108:111], off
	s_waitcnt vmcnt(7)
	v_permlane32_swap_b32_e32 v72, v74
	v_permlane32_swap_b32_e32 v73, v75
	v_lshlrev_b32_e32 v120, 16, v72
	v_and_b32_e32 v121, 0xffff0000, v72
	v_lshlrev_b32_e32 v122, 16, v73
	v_and_b32_e32 v123, 0xffff0000, v73
	v_mul_f32_e32 v116, v58, v120
	v_mul_f32_e32 v117, v59, v121
	v_mul_f32_e32 v118, v60, v122
	v_mul_f32_e32 v119, v61, v123
	v_cvt_pk_bf16_f32 v112, v116, v117
	v_cvt_pk_bf16_f32 v113, v118, v119
	v_lshlrev_b32_e32 v120, 16, v74
	v_and_b32_e32 v121, 0xffff0000, v74
	v_lshlrev_b32_e32 v122, 16, v75
	v_and_b32_e32 v123, 0xffff0000, v75
	v_mul_f32_e32 v116, v62, v120
	v_mul_f32_e32 v117, v63, v121
	v_mul_f32_e32 v118, v64, v122
	v_mul_f32_e32 v119, v65, v123
	v_cvt_pk_bf16_f32 v114, v116, v117
	v_cvt_pk_bf16_f32 v115, v118, v119
	s_nop 1
	v_permlane32_swap_b32_e32 v112, v114
	v_permlane32_swap_b32_e32 v113, v115
	global_store_dwordx4 v[106:107], v[112:115], off offset:32
	s_waitcnt vmcnt(7)
	v_permlane32_swap_b32_e32 v76, v78
	v_permlane32_swap_b32_e32 v77, v79
	v_lshlrev_b32_e32 v120, 16, v76
	v_and_b32_e32 v121, 0xffff0000, v76
	v_lshlrev_b32_e32 v122, 16, v77
	v_and_b32_e32 v123, 0xffff0000, v77
	v_mul_f32_e32 v116, v34, v120
	v_mul_f32_e32 v117, v35, v121
	v_mul_f32_e32 v118, v36, v122
	v_mul_f32_e32 v119, v37, v123
	v_cvt_pk_bf16_f32 v108, v116, v117
	v_cvt_pk_bf16_f32 v109, v118, v119
	v_lshlrev_b32_e32 v120, 16, v78
	v_and_b32_e32 v121, 0xffff0000, v78
	v_lshlrev_b32_e32 v122, 16, v79
	v_and_b32_e32 v123, 0xffff0000, v79
	v_mul_f32_e32 v116, v38, v120
	v_mul_f32_e32 v117, v39, v121
	v_mul_f32_e32 v118, v40, v122
	v_mul_f32_e32 v119, v41, v123
	v_cvt_pk_bf16_f32 v110, v116, v117
	v_cvt_pk_bf16_f32 v111, v118, v119
	s_nop 1
	v_permlane32_swap_b32_e32 v108, v110
	v_permlane32_swap_b32_e32 v109, v111
	global_store_dwordx4 v[106:107], v[108:111], off offset:64
	s_waitcnt vmcnt(7)
	v_permlane32_swap_b32_e32 v80, v82
	v_permlane32_swap_b32_e32 v81, v83
	v_lshlrev_b32_e32 v120, 16, v80
	v_and_b32_e32 v121, 0xffff0000, v80
	v_lshlrev_b32_e32 v122, 16, v81
	v_and_b32_e32 v123, 0xffff0000, v81
	v_mul_f32_e32 v116, v42, v120
	v_mul_f32_e32 v117, v43, v121
	v_mul_f32_e32 v118, v44, v122
	v_mul_f32_e32 v119, v45, v123
	v_cvt_pk_bf16_f32 v112, v116, v117
	v_cvt_pk_bf16_f32 v113, v118, v119
	v_lshlrev_b32_e32 v120, 16, v82
	v_and_b32_e32 v121, 0xffff0000, v82
	v_lshlrev_b32_e32 v122, 16, v83
	v_and_b32_e32 v123, 0xffff0000, v83
	v_mul_f32_e32 v116, v46, v120
	v_mul_f32_e32 v117, v47, v121
	v_mul_f32_e32 v118, v48, v122
	v_mul_f32_e32 v119, v49, v123
	v_cvt_pk_bf16_f32 v114, v116, v117
	v_cvt_pk_bf16_f32 v115, v118, v119
	s_nop 1
	v_permlane32_swap_b32_e32 v112, v114
	v_permlane32_swap_b32_e32 v113, v115
	global_store_dwordx4 v[106:107], v[112:115], off offset:96
	s_waitcnt vmcnt(7)
	v_permlane32_swap_b32_e32 v84, v86
	v_permlane32_swap_b32_e32 v85, v87
	v_lshlrev_b32_e32 v120, 16, v84
	v_and_b32_e32 v121, 0xffff0000, v84
	v_lshlrev_b32_e32 v122, 16, v85
	v_and_b32_e32 v123, 0xffff0000, v85
	v_mul_f32_e32 v116, v18, v120
	v_mul_f32_e32 v117, v19, v121
	v_mul_f32_e32 v118, v20, v122
	v_mul_f32_e32 v119, v21, v123
	v_cvt_pk_bf16_f32 v108, v116, v117
	v_cvt_pk_bf16_f32 v109, v118, v119
	v_lshlrev_b32_e32 v120, 16, v86
	v_and_b32_e32 v121, 0xffff0000, v86
	v_lshlrev_b32_e32 v122, 16, v87
	v_and_b32_e32 v123, 0xffff0000, v87
	v_mul_f32_e32 v116, v22, v120
	v_mul_f32_e32 v117, v23, v121
	v_mul_f32_e32 v118, v24, v122
	v_mul_f32_e32 v119, v25, v123
	v_cvt_pk_bf16_f32 v110, v116, v117
	v_cvt_pk_bf16_f32 v111, v118, v119
	s_nop 1
	v_permlane32_swap_b32_e32 v108, v110
	v_permlane32_swap_b32_e32 v109, v111
	global_store_dwordx4 v[106:107], v[108:111], off offset:128
	s_waitcnt vmcnt(7)
	v_permlane32_swap_b32_e32 v88, v90
	v_permlane32_swap_b32_e32 v89, v91
	v_lshlrev_b32_e32 v120, 16, v88
	v_and_b32_e32 v121, 0xffff0000, v88
	v_lshlrev_b32_e32 v122, 16, v89
	v_and_b32_e32 v123, 0xffff0000, v89
	v_mul_f32_e32 v116, v26, v120
	v_mul_f32_e32 v117, v27, v121
	v_mul_f32_e32 v118, v28, v122
	v_mul_f32_e32 v119, v29, v123
	v_cvt_pk_bf16_f32 v112, v116, v117
	v_cvt_pk_bf16_f32 v113, v118, v119
	v_lshlrev_b32_e32 v120, 16, v90
	v_and_b32_e32 v121, 0xffff0000, v90
	v_lshlrev_b32_e32 v122, 16, v91
	v_and_b32_e32 v123, 0xffff0000, v91
	v_mul_f32_e32 v116, v30, v120
	v_mul_f32_e32 v117, v31, v121
	v_mul_f32_e32 v118, v32, v122
	v_mul_f32_e32 v119, v33, v123
	v_cvt_pk_bf16_f32 v114, v116, v117
	v_cvt_pk_bf16_f32 v115, v118, v119
	s_nop 1
	v_permlane32_swap_b32_e32 v112, v114
	v_permlane32_swap_b32_e32 v113, v115
	global_store_dwordx4 v[106:107], v[112:115], off offset:160
	s_waitcnt vmcnt(7)
	v_permlane32_swap_b32_e32 v92, v94
	v_permlane32_swap_b32_e32 v93, v95
	v_lshlrev_b32_e32 v120, 16, v92
	v_and_b32_e32 v121, 0xffff0000, v92
	v_lshlrev_b32_e32 v122, 16, v93
	v_and_b32_e32 v123, 0xffff0000, v93
	v_mul_f32_e32 v116, v2, v120
	v_mul_f32_e32 v117, v3, v121
	v_mul_f32_e32 v118, v4, v122
	v_mul_f32_e32 v119, v5, v123
	v_cvt_pk_bf16_f32 v108, v116, v117
	v_cvt_pk_bf16_f32 v109, v118, v119
	v_lshlrev_b32_e32 v120, 16, v94
	v_and_b32_e32 v121, 0xffff0000, v94
	v_lshlrev_b32_e32 v122, 16, v95
	v_and_b32_e32 v123, 0xffff0000, v95
	v_mul_f32_e32 v116, v6, v120
	v_mul_f32_e32 v117, v7, v121
	v_mul_f32_e32 v118, v8, v122
	v_mul_f32_e32 v119, v9, v123
	v_cvt_pk_bf16_f32 v110, v116, v117
	v_cvt_pk_bf16_f32 v111, v118, v119
	s_nop 1
	v_permlane32_swap_b32_e32 v108, v110
	v_permlane32_swap_b32_e32 v109, v111
	global_store_dwordx4 v[106:107], v[108:111], off offset:192
	s_waitcnt vmcnt(7)
	v_permlane32_swap_b32_e32 v96, v98
	v_permlane32_swap_b32_e32 v97, v99
	v_lshlrev_b32_e32 v120, 16, v96
	v_and_b32_e32 v121, 0xffff0000, v96
	v_lshlrev_b32_e32 v122, 16, v97
	v_and_b32_e32 v123, 0xffff0000, v97
	v_mul_f32_e32 v116, v10, v120
	v_mul_f32_e32 v117, v11, v121
	v_mul_f32_e32 v118, v12, v122
	v_mul_f32_e32 v119, v13, v123
	v_cvt_pk_bf16_f32 v112, v116, v117
	v_cvt_pk_bf16_f32 v113, v118, v119
	v_lshlrev_b32_e32 v120, 16, v98
	v_and_b32_e32 v121, 0xffff0000, v98
	v_lshlrev_b32_e32 v122, 16, v99
	v_and_b32_e32 v123, 0xffff0000, v99
	v_mul_f32_e32 v116, v14, v120
	v_mul_f32_e32 v117, v15, v121
	v_mul_f32_e32 v118, v16, v122
	v_mul_f32_e32 v119, v17, v123
	v_cvt_pk_bf16_f32 v114, v116, v117
	v_cvt_pk_bf16_f32 v115, v118, v119
	s_nop 1
	v_permlane32_swap_b32_e32 v112, v114
	v_permlane32_swap_b32_e32 v113, v115
	global_store_dwordx4 v[106:107], v[112:115], off offset:224
	s_add_i32 s17, s17, s20
	s_cmpk_gt_i32 s17, 0x7ff
	s_cbranch_scc1 .LBB0_49

.LBB0_57:
	s_or_b64 exec, exec, s[0:1]
	s_lshl_b64 s[0:1], s[28:29], 1
	s_add_u32 s8, s37, s0
	s_addc_u32 s9, s38, s1
	v_mov_b32_e32 v66, v193
	s_add_u32 s8, s8, s26
	s_addc_u32 s9, s9, s27
	v_permlane32_swap_b32_e32 v193, v66
	v_add_f32_e32 v100, v193, v66
	v_mov_b32_e32 v193, v1
	v_lshl_add_u64 v[66:67], s[8:9], 0, v[192:193]
	v_lshlrev_b64 v[106:107], 1, v[186:187]
	v_lshl_add_u64 v[66:67], v[66:67], 0, v[106:107]
	v_lshl_add_u64 v[66:67], v[66:67], 0, v[106:107]
	global_load_dwordx4 v[68:71], v[66:67], off
	global_load_dwordx4 v[72:75], v[66:67], off offset:32
	global_load_dwordx4 v[76:79], v[66:67], off offset:64
	global_load_dwordx4 v[80:83], v[66:67], off offset:96
	global_load_dwordx4 v[84:87], v[66:67], off offset:128
	global_load_dwordx4 v[88:91], v[66:67], off offset:160
	global_load_dwordx4 v[92:95], v[66:67], off offset:192
	global_load_dwordx4 v[96:99], v[66:67], off offset:224
	v_div_scale_f32 v101, s[8:9], v100, v100, 1.0
	v_rcp_f32_e32 v102, v101
	s_add_u32 s0, s41, s0
	s_addc_u32 s1, s42, s1
	s_add_u32 s0, s0, s26
	s_addc_u32 s1, s1, s27
	v_fma_f32 v103, -v101, v102, 1.0
	v_fmac_f32_e32 v102, v103, v102
	v_div_scale_f32 v103, vcc, 1.0, v100, 1.0
	v_mul_f32_e32 v104, v103, v102
	v_fma_f32 v105, -v101, v104, v103
	v_fmac_f32_e32 v104, v105, v102
	v_fma_f32 v101, -v101, v104, v103
	v_div_fmas_f32 v101, v101, v102, v104
	v_div_fixup_f32 v100, v101, v100, 1.0
	v_lshl_add_u64 v[124:125], s[0:1], 0, v[192:193]
	v_lshl_add_u64 v[124:125], v[124:125], 0, v[106:107]
	v_lshl_add_u64 v[106:107], v[124:125], 0, v[106:107]
	s_waitcnt vmcnt(7)
	v_permlane32_swap_b32_e32 v68, v70
	v_permlane32_swap_b32_e32 v69, v71
	v_lshlrev_b32_e32 v120, 16, v68
	v_and_b32_e32 v121, 0xffff0000, v68
	v_lshlrev_b32_e32 v122, 16, v69
	v_and_b32_e32 v123, 0xffff0000, v69
	v_mul_f32_e32 v116, v50, v100
	v_mul_f32_e32 v117, v51, v100
	v_mul_f32_e32 v118, v52, v100
	v_mul_f32_e32 v119, v53, v100
	v_mul_f32_e32 v116, v116, v120
	v_mul_f32_e32 v117, v117, v121
	v_mul_f32_e32 v118, v118, v122
	v_mul_f32_e32 v119, v119, v123
	v_cvt_pk_bf16_f32 v108, v116, v117
	v_cvt_pk_bf16_f32 v109, v118, v119
	v_lshlrev_b32_e32 v120, 16, v70
	v_and_b32_e32 v121, 0xffff0000, v70
	v_lshlrev_b32_e32 v122, 16, v71
	v_and_b32_e32 v123, 0xffff0000, v71
	v_mul_f32_e32 v116, v54, v100
	v_mul_f32_e32 v117, v55, v100
	v_mul_f32_e32 v118, v56, v100
	v_mul_f32_e32 v119, v57, v100
	v_mul_f32_e32 v116, v116, v120
	v_mul_f32_e32 v117, v117, v121
	v_mul_f32_e32 v118, v118, v122
	v_mul_f32_e32 v119, v119, v123
	v_cvt_pk_bf16_f32 v110, v116, v117
	v_cvt_pk_bf16_f32 v111, v118, v119
	s_nop 1
	v_permlane32_swap_b32_e32 v108, v110
	v_permlane32_swap_b32_e32 v109, v111
	global_store_dwordx4 v[106:107], v[108:111], off
	s_waitcnt vmcnt(7)
	v_permlane32_swap_b32_e32 v72, v74
	v_permlane32_swap_b32_e32 v73, v75
	v_lshlrev_b32_e32 v120, 16, v72
	v_and_b32_e32 v121, 0xffff0000, v72
	v_lshlrev_b32_e32 v122, 16, v73
	v_and_b32_e32 v123, 0xffff0000, v73
	v_mul_f32_e32 v116, v58, v100
	v_mul_f32_e32 v117, v59, v100
	v_mul_f32_e32 v118, v60, v100
	v_mul_f32_e32 v119, v61, v100
	v_mul_f32_e32 v116, v116, v120
	v_mul_f32_e32 v117, v117, v121
	v_mul_f32_e32 v118, v118, v122
	v_mul_f32_e32 v119, v119, v123
	v_cvt_pk_bf16_f32 v112, v116, v117
	v_cvt_pk_bf16_f32 v113, v118, v119
	v_lshlrev_b32_e32 v120, 16, v74
	v_and_b32_e32 v121, 0xffff0000, v74
	v_lshlrev_b32_e32 v122, 16, v75
	v_and_b32_e32 v123, 0xffff0000, v75
	v_mul_f32_e32 v116, v62, v100
	v_mul_f32_e32 v117, v63, v100
	v_mul_f32_e32 v118, v64, v100
	v_mul_f32_e32 v119, v65, v100
	v_mul_f32_e32 v116, v116, v120
	v_mul_f32_e32 v117, v117, v121
	v_mul_f32_e32 v118, v118, v122
	v_mul_f32_e32 v119, v119, v123
	v_cvt_pk_bf16_f32 v114, v116, v117
	v_cvt_pk_bf16_f32 v115, v118, v119
	s_nop 1
	v_permlane32_swap_b32_e32 v112, v114
	v_permlane32_swap_b32_e32 v113, v115
	global_store_dwordx4 v[106:107], v[112:115], off offset:32
	s_waitcnt vmcnt(7)
	v_permlane32_swap_b32_e32 v76, v78
	v_permlane32_swap_b32_e32 v77, v79
	v_lshlrev_b32_e32 v120, 16, v76
	v_and_b32_e32 v121, 0xffff0000, v76
	v_lshlrev_b32_e32 v122, 16, v77
	v_and_b32_e32 v123, 0xffff0000, v77
	v_mul_f32_e32 v116, v34, v100
	v_mul_f32_e32 v117, v35, v100
	v_mul_f32_e32 v118, v36, v100
	v_mul_f32_e32 v119, v37, v100
	v_mul_f32_e32 v116, v116, v120
	v_mul_f32_e32 v117, v117, v121
	v_mul_f32_e32 v118, v118, v122
	v_mul_f32_e32 v119, v119, v123
	v_cvt_pk_bf16_f32 v108, v116, v117
	v_cvt_pk_bf16_f32 v109, v118, v119
	v_lshlrev_b32_e32 v120, 16, v78
	v_and_b32_e32 v121, 0xffff0000, v78
	v_lshlrev_b32_e32 v122, 16, v79
	v_and_b32_e32 v123, 0xffff0000, v79
	v_mul_f32_e32 v116, v38, v100
	v_mul_f32_e32 v117, v39, v100
	v_mul_f32_e32 v118, v40, v100
	v_mul_f32_e32 v119, v41, v100
	v_mul_f32_e32 v116, v116, v120
	v_mul_f32_e32 v117, v117, v121
	v_mul_f32_e32 v118, v118, v122
	v_mul_f32_e32 v119, v119, v123
	v_cvt_pk_bf16_f32 v110, v116, v117
	v_cvt_pk_bf16_f32 v111, v118, v119
	s_nop 1
	v_permlane32_swap_b32_e32 v108, v110
	v_permlane32_swap_b32_e32 v109, v111
	global_store_dwordx4 v[106:107], v[108:111], off offset:64
	s_waitcnt vmcnt(7)
	v_permlane32_swap_b32_e32 v80, v82
	v_permlane32_swap_b32_e32 v81, v83
	v_lshlrev_b32_e32 v120, 16, v80
	v_and_b32_e32 v121, 0xffff0000, v80
	v_lshlrev_b32_e32 v122, 16, v81
	v_and_b32_e32 v123, 0xffff0000, v81
	v_mul_f32_e32 v116, v42, v100
	v_mul_f32_e32 v117, v43, v100
	v_mul_f32_e32 v118, v44, v100
	v_mul_f32_e32 v119, v45, v100
	v_mul_f32_e32 v116, v116, v120
	v_mul_f32_e32 v117, v117, v121
	v_mul_f32_e32 v118, v118, v122
	v_mul_f32_e32 v119, v119, v123
	v_cvt_pk_bf16_f32 v112, v116, v117
	v_cvt_pk_bf16_f32 v113, v118, v119
	v_lshlrev_b32_e32 v120, 16, v82
	v_and_b32_e32 v121, 0xffff0000, v82
	v_lshlrev_b32_e32 v122, 16, v83
	v_and_b32_e32 v123, 0xffff0000, v83
	v_mul_f32_e32 v116, v46, v100
	v_mul_f32_e32 v117, v47, v100
	v_mul_f32_e32 v118, v48, v100
	v_mul_f32_e32 v119, v49, v100
	v_mul_f32_e32 v116, v116, v120
	v_mul_f32_e32 v117, v117, v121
	v_mul_f32_e32 v118, v118, v122
	v_mul_f32_e32 v119, v119, v123
	v_cvt_pk_bf16_f32 v114, v116, v117
	v_cvt_pk_bf16_f32 v115, v118, v119
	s_nop 1
	v_permlane32_swap_b32_e32 v112, v114
	v_permlane32_swap_b32_e32 v113, v115
	global_store_dwordx4 v[106:107], v[112:115], off offset:96
	s_waitcnt vmcnt(7)
	v_permlane32_swap_b32_e32 v84, v86
	v_permlane32_swap_b32_e32 v85, v87
	v_lshlrev_b32_e32 v120, 16, v84
	v_and_b32_e32 v121, 0xffff0000, v84
	v_lshlrev_b32_e32 v122, 16, v85
	v_and_b32_e32 v123, 0xffff0000, v85
	v_mul_f32_e32 v116, v18, v100
	v_mul_f32_e32 v117, v19, v100
	v_mul_f32_e32 v118, v20, v100
	v_mul_f32_e32 v119, v21, v100
	v_mul_f32_e32 v116, v116, v120
	v_mul_f32_e32 v117, v117, v121
	v_mul_f32_e32 v118, v118, v122
	v_mul_f32_e32 v119, v119, v123
	v_cvt_pk_bf16_f32 v108, v116, v117
	v_cvt_pk_bf16_f32 v109, v118, v119
	v_lshlrev_b32_e32 v120, 16, v86
	v_and_b32_e32 v121, 0xffff0000, v86
	v_lshlrev_b32_e32 v122, 16, v87
	v_and_b32_e32 v123, 0xffff0000, v87
	v_mul_f32_e32 v116, v22, v100
	v_mul_f32_e32 v117, v23, v100
	v_mul_f32_e32 v118, v24, v100
	v_mul_f32_e32 v119, v25, v100
	v_mul_f32_e32 v116, v116, v120
	v_mul_f32_e32 v117, v117, v121
	v_mul_f32_e32 v118, v118, v122
	v_mul_f32_e32 v119, v119, v123
	v_cvt_pk_bf16_f32 v110, v116, v117
	v_cvt_pk_bf16_f32 v111, v118, v119
	s_nop 1
	v_permlane32_swap_b32_e32 v108, v110
	v_permlane32_swap_b32_e32 v109, v111
	global_store_dwordx4 v[106:107], v[108:111], off offset:128
	s_waitcnt vmcnt(7)
	v_permlane32_swap_b32_e32 v88, v90
	v_permlane32_swap_b32_e32 v89, v91
	v_lshlrev_b32_e32 v120, 16, v88
	v_and_b32_e32 v121, 0xffff0000, v88
	v_lshlrev_b32_e32 v122, 16, v89
	v_and_b32_e32 v123, 0xffff0000, v89
	v_mul_f32_e32 v116, v26, v100
	v_mul_f32_e32 v117, v27, v100
	v_mul_f32_e32 v118, v28, v100
	v_mul_f32_e32 v119, v29, v100
	v_mul_f32_e32 v116, v116, v120
	v_mul_f32_e32 v117, v117, v121
	v_mul_f32_e32 v118, v118, v122
	v_mul_f32_e32 v119, v119, v123
	v_cvt_pk_bf16_f32 v112, v116, v117
	v_cvt_pk_bf16_f32 v113, v118, v119
	v_lshlrev_b32_e32 v120, 16, v90
	v_and_b32_e32 v121, 0xffff0000, v90
	v_lshlrev_b32_e32 v122, 16, v91
	v_and_b32_e32 v123, 0xffff0000, v91
	v_mul_f32_e32 v116, v30, v100
	v_mul_f32_e32 v117, v31, v100
	v_mul_f32_e32 v118, v32, v100
	v_mul_f32_e32 v119, v33, v100
	v_mul_f32_e32 v116, v116, v120
	v_mul_f32_e32 v117, v117, v121
	v_mul_f32_e32 v118, v118, v122
	v_mul_f32_e32 v119, v119, v123
	v_cvt_pk_bf16_f32 v114, v116, v117
	v_cvt_pk_bf16_f32 v115, v118, v119
	s_nop 1
	v_permlane32_swap_b32_e32 v112, v114
	v_permlane32_swap_b32_e32 v113, v115
	global_store_dwordx4 v[106:107], v[112:115], off offset:160
	s_waitcnt vmcnt(7)
	v_permlane32_swap_b32_e32 v92, v94
	v_permlane32_swap_b32_e32 v93, v95
	v_lshlrev_b32_e32 v120, 16, v92
	v_and_b32_e32 v121, 0xffff0000, v92
	v_lshlrev_b32_e32 v122, 16, v93
	v_and_b32_e32 v123, 0xffff0000, v93
	v_mul_f32_e32 v116, v2, v100
	v_mul_f32_e32 v117, v3, v100
	v_mul_f32_e32 v118, v4, v100
	v_mul_f32_e32 v119, v5, v100
	v_mul_f32_e32 v116, v116, v120
	v_mul_f32_e32 v117, v117, v121
	v_mul_f32_e32 v118, v118, v122
	v_mul_f32_e32 v119, v119, v123
	v_cvt_pk_bf16_f32 v108, v116, v117
	v_cvt_pk_bf16_f32 v109, v118, v119
	v_lshlrev_b32_e32 v120, 16, v94
	v_and_b32_e32 v121, 0xffff0000, v94
	v_lshlrev_b32_e32 v122, 16, v95
	v_and_b32_e32 v123, 0xffff0000, v95
	v_mul_f32_e32 v116, v6, v100
	v_mul_f32_e32 v117, v7, v100
	v_mul_f32_e32 v118, v8, v100
	v_mul_f32_e32 v119, v9, v100
	v_mul_f32_e32 v116, v116, v120
	v_mul_f32_e32 v117, v117, v121
	v_mul_f32_e32 v118, v118, v122
	v_mul_f32_e32 v119, v119, v123
	v_cvt_pk_bf16_f32 v110, v116, v117
	v_cvt_pk_bf16_f32 v111, v118, v119
	s_nop 1
	v_permlane32_swap_b32_e32 v108, v110
	v_permlane32_swap_b32_e32 v109, v111
	global_store_dwordx4 v[106:107], v[108:111], off offset:192
	s_waitcnt vmcnt(7)
	v_permlane32_swap_b32_e32 v96, v98
	v_permlane32_swap_b32_e32 v97, v99
	v_lshlrev_b32_e32 v120, 16, v96
	v_and_b32_e32 v121, 0xffff0000, v96
	v_lshlrev_b32_e32 v122, 16, v97
	v_and_b32_e32 v123, 0xffff0000, v97
	v_mul_f32_e32 v116, v10, v100
	v_mul_f32_e32 v117, v11, v100
	v_mul_f32_e32 v118, v12, v100
	v_mul_f32_e32 v119, v13, v100
	v_mul_f32_e32 v116, v116, v120
	v_mul_f32_e32 v117, v117, v121
	v_mul_f32_e32 v118, v118, v122
	v_mul_f32_e32 v119, v119, v123
	v_cvt_pk_bf16_f32 v112, v116, v117
	v_cvt_pk_bf16_f32 v113, v118, v119
	v_lshlrev_b32_e32 v120, 16, v98
	v_and_b32_e32 v121, 0xffff0000, v98
	v_lshlrev_b32_e32 v122, 16, v99
	v_and_b32_e32 v123, 0xffff0000, v99
	v_mul_f32_e32 v116, v14, v100
	v_mul_f32_e32 v117, v15, v100
	v_mul_f32_e32 v118, v16, v100
	v_mul_f32_e32 v119, v17, v100
	v_mul_f32_e32 v116, v116, v120
	v_mul_f32_e32 v117, v117, v121
	v_mul_f32_e32 v118, v118, v122
	v_mul_f32_e32 v119, v119, v123
	v_cvt_pk_bf16_f32 v114, v116, v117
	v_cvt_pk_bf16_f32 v115, v118, v119
	s_nop 1
	v_permlane32_swap_b32_e32 v112, v114
	v_permlane32_swap_b32_e32 v113, v115
	global_store_dwordx4 v[106:107], v[112:115], off offset:224
	s_add_i32 s2, s2, s20
	s_cmpk_gt_i32 s2, 0x7ff
	s_barrier
	s_cbranch_scc1 .LBB0_99

.LBB0_123:
	ds_read2st64_b32 v[4:5], v250 offset1:1
	ds_read2st64_b32 v[6:7], v250 offset0:32 offset1:33
	ds_read2st64_b32 v[8:9], v250 offset0:2 offset1:3
	ds_read2st64_b32 v[12:13], v250 offset0:4 offset1:5
	ds_read2st64_b32 v[16:17], v250 offset0:6 offset1:7
	s_waitcnt lgkmcnt(4)
	v_and_b32_e32 v3, 0x7fffffff, v4
	s_waitcnt lgkmcnt(3)
	v_and_b32_e32 v2, 0x7fffffff, v6
	v_xor_b32_e32 v20, -1, v6
	v_pk_add_f32 v[2:3], v[2:3], 0 neg_lo:[1,1] neg_hi:[1,1]
	v_cmp_gt_i32_e32 vcc, 0, v6
	v_xor_b32_e32 v0, -1, v4
	s_or_b32 s2, s10, 1
	v_cndmask_b32_e32 v6, v2, v20, vcc
	v_cmp_gt_i32_e32 vcc, 0, v4
	v_and_b32_e32 v21, 0x7fffffff, v5
	v_and_b32_e32 v20, 0x7fffffff, v7
	v_cndmask_b32_e32 v0, v3, v0, vcc
	v_cmp_ge_i32_e32 vcc, s10, v229
	v_xor_b32_e32 v4, -1, v7
	v_pk_add_f32 v[20:21], v[20:21], 0 neg_lo:[1,1] neg_hi:[1,1]
	v_cndmask_b32_e32 v2, 0, v0, vcc
	v_cmp_ge_i32_e32 vcc, s2, v178
	ds_read2st64_b32 v[10:11], v250 offset0:34 offset1:35
	ds_read2st64_b32 v[14:15], v250 offset0:36 offset1:37
	ds_read2st64_b32 v[18:19], v250 offset0:38 offset1:39
	v_cndmask_b32_e32 v3, 0, v6, vcc
	v_cmp_gt_i32_e32 vcc, 0, v7
	v_xor_b32_e32 v0, -1, v5
	s_waitcnt lgkmcnt(5)
	v_and_b32_e32 v7, 0x7fffffff, v8
	v_cndmask_b32_e32 v6, v20, v4, vcc
	v_cmp_gt_i32_e32 vcc, 0, v5
	s_waitcnt lgkmcnt(2)
	v_xor_b32_e32 v20, -1, v10
	s_cmpk_gt_i32 s10, 0xfe
	v_cndmask_b32_e32 v0, v21, v0, vcc
	v_cmp_ge_i32_e32 vcc, s10, v227
	v_and_b32_e32 v21, 0x7fffffff, v9
	s_mov_b32 s11, 1
	v_cndmask_b32_e32 v4, 0, v0, vcc
	v_cmp_ge_i32_e32 vcc, s2, v162
	v_xor_b32_e32 v0, -1, v8
	s_mov_b32 s44, 1
	v_cndmask_b32_e32 v5, 0, v6, vcc
	v_and_b32_e32 v6, 0x7fffffff, v10
	v_pk_add_f32 v[6:7], v[6:7], 0 neg_lo:[1,1] neg_hi:[1,1]
	v_cmp_gt_i32_e32 vcc, 0, v10
	s_nop 1
	v_cndmask_b32_e32 v10, v6, v20, vcc
	v_cmp_gt_i32_e32 vcc, 0, v8
	v_and_b32_e32 v20, 0x7fffffff, v11
	v_xor_b32_e32 v8, -1, v11
	v_cndmask_b32_e32 v0, v7, v0, vcc
	v_cmp_ge_i32_e32 vcc, s10, v225
	v_pk_add_f32 v[20:21], v[20:21], 0 neg_lo:[1,1] neg_hi:[1,1]
	s_nop 0
	v_cndmask_b32_e32 v6, 0, v0, vcc
	v_cmp_ge_i32_e32 vcc, s2, v164
	v_xor_b32_e32 v0, -1, v9
	s_nop 0
	v_cndmask_b32_e32 v7, 0, v10, vcc
	v_cmp_gt_i32_e32 vcc, 0, v11
	v_and_b32_e32 v11, 0x7fffffff, v12
	s_nop 0
	v_cndmask_b32_e32 v10, v20, v8, vcc
	v_cmp_gt_i32_e32 vcc, 0, v9
	s_waitcnt lgkmcnt(1)
	v_xor_b32_e32 v20, -1, v14
	v_cndmask_b32_e32 v0, v21, v0, vcc
	v_cmp_ge_i32_e32 vcc, s10, v223
	v_and_b32_e32 v21, 0x7fffffff, v13
	s_nop 0
	v_cndmask_b32_e32 v8, 0, v0, vcc
	v_cmp_ge_i32_e32 vcc, s2, v166
	v_xor_b32_e32 v0, -1, v12
	s_nop 0
	v_cndmask_b32_e32 v9, 0, v10, vcc
	v_and_b32_e32 v10, 0x7fffffff, v14
	v_pk_add_f32 v[10:11], v[10:11], 0 neg_lo:[1,1] neg_hi:[1,1]
	v_cmp_gt_i32_e32 vcc, 0, v14
	s_nop 1
	v_cndmask_b32_e32 v14, v10, v20, vcc
	v_cmp_gt_i32_e32 vcc, 0, v12
	v_and_b32_e32 v20, 0x7fffffff, v15
	v_xor_b32_e32 v12, -1, v15
	v_cndmask_b32_e32 v0, v11, v0, vcc
	v_cmp_ge_i32_e32 vcc, s10, v221
	v_pk_add_f32 v[20:21], v[20:21], 0 neg_lo:[1,1] neg_hi:[1,1]
	s_nop 0
	v_cndmask_b32_e32 v10, 0, v0, vcc
	v_cmp_ge_i32_e32 vcc, s2, v168
	v_xor_b32_e32 v0, -1, v13
	s_nop 0
	v_cndmask_b32_e32 v11, 0, v14, vcc
	v_cmp_gt_i32_e32 vcc, 0, v15
	v_and_b32_e32 v15, 0x7fffffff, v16
	s_waitcnt lgkmcnt(0)
	v_and_b32_e32 v14, 0x7fffffff, v18
	v_cndmask_b32_e32 v12, v20, v12, vcc
	v_cmp_gt_i32_e32 vcc, 0, v13
	v_xor_b32_e32 v20, -1, v18
	v_pk_add_f32 v[14:15], v[14:15], 0 neg_lo:[1,1] neg_hi:[1,1]
	v_cndmask_b32_e32 v0, v21, v0, vcc
	v_cmp_ge_i32_e32 vcc, s10, v219
	v_and_b32_e32 v21, 0x7fffffff, v17
	s_nop 0
	v_cndmask_b32_e32 v13, 0, v0, vcc
	v_cmp_ge_i32_e32 vcc, s2, v170
	v_xor_b32_e32 v0, -1, v16
	s_nop 0
	v_cndmask_b32_e32 v12, 0, v12, vcc
	v_cmp_gt_i32_e32 vcc, 0, v18
	s_nop 1
	v_cndmask_b32_e32 v14, v14, v20, vcc
	v_cmp_gt_i32_e32 vcc, 0, v16
	v_and_b32_e32 v20, 0x7fffffff, v19
	v_xor_b32_e32 v16, -1, v19
	v_cndmask_b32_e32 v0, v15, v0, vcc
	v_cmp_ge_i32_e32 vcc, s10, v217
	v_pk_add_f32 v[20:21], v[20:21], 0 neg_lo:[1,1] neg_hi:[1,1]
	s_nop 0
	v_cndmask_b32_e32 v15, 0, v0, vcc
	v_cmp_ge_i32_e32 vcc, s2, v172
	v_xor_b32_e32 v0, -1, v17
	s_nop 0
	v_cndmask_b32_e32 v14, 0, v14, vcc
	v_cmp_gt_i32_e32 vcc, 0, v19
	s_nop 1
	v_cndmask_b32_e32 v16, v20, v16, vcc
	v_cmp_gt_i32_e32 vcc, 0, v17
	s_nop 1
	v_cndmask_b32_e32 v0, v21, v0, vcc
	ds_read2st64_b32 v[20:21], v250 offset0:8 offset1:9
	ds_read2st64_b32 v[22:23], v250 offset0:40 offset1:41
	ds_read2st64_b32 v[24:25], v250 offset0:10 offset1:11
	ds_read2st64_b32 v[28:29], v250 offset0:12 offset1:13
	ds_read2st64_b32 v[32:33], v250 offset0:14 offset1:15
	v_cmp_ge_i32_e32 vcc, s10, v215
	s_waitcnt lgkmcnt(4)
	v_and_b32_e32 v19, 0x7fffffff, v20
	s_waitcnt lgkmcnt(3)
	v_and_b32_e32 v18, 0x7fffffff, v22
	v_cndmask_b32_e32 v17, 0, v0, vcc
	v_cmp_ge_i32_e32 vcc, s2, v182
	v_xor_b32_e32 v36, -1, v22
	v_pk_add_f32 v[18:19], v[18:19], 0 neg_lo:[1,1] neg_hi:[1,1]
	v_cndmask_b32_e32 v16, 0, v16, vcc
	v_cmp_gt_i32_e32 vcc, 0, v22
	v_xor_b32_e32 v0, -1, v20
	v_and_b32_e32 v37, 0x7fffffff, v21
	v_cndmask_b32_e32 v18, v18, v36, vcc
	v_cmp_gt_i32_e32 vcc, 0, v20
	v_and_b32_e32 v36, 0x7fffffff, v23
	ds_read2st64_b32 v[26:27], v250 offset0:42 offset1:43
	ds_read2st64_b32 v[30:31], v250 offset0:44 offset1:45
	ds_read2st64_b32 v[34:35], v250 offset0:46 offset1:47
	v_cndmask_b32_e32 v0, v19, v0, vcc
	v_cmp_ge_i32_e32 vcc, s10, v213
	v_xor_b32_e32 v20, -1, v23
	v_pk_add_f32 v[36:37], v[36:37], 0 neg_lo:[1,1] neg_hi:[1,1]
	v_cndmask_b32_e32 v19, 0, v0, vcc
	v_cmp_ge_i32_e32 vcc, s2, v184
	v_xor_b32_e32 v0, -1, v21
	s_nop 0
	v_cndmask_b32_e32 v18, 0, v18, vcc
	v_cmp_gt_i32_e32 vcc, 0, v23
	s_nop 1
	v_cndmask_b32_e32 v20, v36, v20, vcc
	v_cmp_gt_i32_e32 vcc, 0, v21
	s_waitcnt lgkmcnt(2)
	v_and_b32_e32 v36, 0x7fffffff, v26
	v_cndmask_b32_e32 v0, v37, v0, vcc
	v_cmp_ge_i32_e32 vcc, s10, v211
	v_and_b32_e32 v37, 0x7fffffff, v24
	v_pk_add_f32 v[36:37], v[36:37], 0 neg_lo:[1,1] neg_hi:[1,1]
	v_cndmask_b32_e32 v22, 0, v0, vcc
	v_cmp_ge_i32_e32 vcc, s2, v186
	v_xor_b32_e32 v0, -1, v24
	s_nop 0
	v_cndmask_b32_e32 v21, 0, v20, vcc
	v_xor_b32_e32 v20, -1, v26
	v_cmp_gt_i32_e32 vcc, 0, v26
	s_nop 1
	v_cndmask_b32_e32 v20, v36, v20, vcc
	v_cmp_gt_i32_e32 vcc, 0, v24
	v_and_b32_e32 v36, 0x7fffffff, v27
	s_nop 0
	v_cndmask_b32_e32 v0, v37, v0, vcc
	v_cmp_ge_i32_e32 vcc, s10, v209
	v_and_b32_e32 v37, 0x7fffffff, v25
	v_pk_add_f32 v[36:37], v[36:37], 0 neg_lo:[1,1] neg_hi:[1,1]
	v_cndmask_b32_e32 v24, 0, v0, vcc
	v_cmp_ge_i32_e32 vcc, s2, v188
	v_xor_b32_e32 v0, -1, v25
	s_nop 0
	v_cndmask_b32_e32 v23, 0, v20, vcc
	v_xor_b32_e32 v20, -1, v27
	v_cmp_gt_i32_e32 vcc, 0, v27
	s_nop 1
	v_cndmask_b32_e32 v20, v36, v20, vcc
	v_cmp_gt_i32_e32 vcc, 0, v25
	s_waitcnt lgkmcnt(1)
	v_and_b32_e32 v36, 0x7fffffff, v30
	v_cndmask_b32_e32 v0, v37, v0, vcc
	v_cmp_ge_i32_e32 vcc, s10, v207
	v_and_b32_e32 v37, 0x7fffffff, v28
	v_pk_add_f32 v[36:37], v[36:37], 0 neg_lo:[1,1] neg_hi:[1,1]
	v_cndmask_b32_e32 v26, 0, v0, vcc
	v_cmp_ge_i32_e32 vcc, s2, v190
	v_xor_b32_e32 v0, -1, v28
	s_nop 0
	v_cndmask_b32_e32 v25, 0, v20, vcc
	v_xor_b32_e32 v20, -1, v30
	v_cmp_gt_i32_e32 vcc, 0, v30
	s_nop 1
	v_cndmask_b32_e32 v20, v36, v20, vcc
	v_cmp_gt_i32_e32 vcc, 0, v28
	v_and_b32_e32 v36, 0x7fffffff, v31
	s_nop 0
	v_cndmask_b32_e32 v0, v37, v0, vcc
	v_cmp_ge_i32_e32 vcc, s10, v205
	v_and_b32_e32 v37, 0x7fffffff, v29
	v_pk_add_f32 v[36:37], v[36:37], 0 neg_lo:[1,1] neg_hi:[1,1]
	v_cndmask_b32_e32 v28, 0, v0, vcc
	v_cmp_ge_i32_e32 vcc, s2, v192
	v_xor_b32_e32 v0, -1, v29
	s_nop 0
	v_cndmask_b32_e32 v27, 0, v20, vcc
	v_xor_b32_e32 v20, -1, v31
	v_cmp_gt_i32_e32 vcc, 0, v31
	s_nop 1
	v_cndmask_b32_e32 v20, v36, v20, vcc
	v_cmp_gt_i32_e32 vcc, 0, v29
	s_waitcnt lgkmcnt(0)
	v_and_b32_e32 v36, 0x7fffffff, v34
	v_cndmask_b32_e32 v0, v37, v0, vcc
	v_cmp_ge_i32_e32 vcc, s10, v203
	v_and_b32_e32 v37, 0x7fffffff, v32
	v_pk_add_f32 v[36:37], v[36:37], 0 neg_lo:[1,1] neg_hi:[1,1]
	v_cndmask_b32_e32 v30, 0, v0, vcc
	v_cmp_ge_i32_e32 vcc, s2, v194
	v_xor_b32_e32 v0, -1, v32
	s_nop 0
	v_cndmask_b32_e32 v29, 0, v20, vcc
	v_xor_b32_e32 v20, -1, v34
	v_cmp_gt_i32_e32 vcc, 0, v34
	s_nop 1
	v_cndmask_b32_e32 v20, v36, v20, vcc
	v_cmp_gt_i32_e32 vcc, 0, v32
	v_and_b32_e32 v36, 0x7fffffff, v35
	s_nop 0
	v_cndmask_b32_e32 v0, v37, v0, vcc
	v_cmp_ge_i32_e32 vcc, s10, v201
	v_and_b32_e32 v37, 0x7fffffff, v33
	v_pk_add_f32 v[36:37], v[36:37], 0 neg_lo:[1,1] neg_hi:[1,1]
	v_cndmask_b32_e32 v32, 0, v0, vcc
	v_cmp_ge_i32_e32 vcc, s2, v196
	v_xor_b32_e32 v0, -1, v33
	s_nop 0
	v_cndmask_b32_e32 v31, 0, v20, vcc
	v_xor_b32_e32 v20, -1, v35
	v_cmp_gt_i32_e32 vcc, 0, v35
	s_nop 1
	v_cndmask_b32_e32 v20, v36, v20, vcc
	v_cmp_gt_i32_e32 vcc, 0, v33
	s_nop 1
	v_cndmask_b32_e32 v0, v37, v0, vcc
	ds_read2st64_b32 v[34:35], v250 offset0:16 offset1:17
	ds_read2st64_b32 v[36:37], v250 offset0:48 offset1:49
	ds_read2st64_b32 v[44:45], v250 offset0:18 offset1:19
	ds_read2st64_b32 v[46:47], v250 offset0:20 offset1:21
	ds_read2st64_b32 v[48:49], v250 offset0:22 offset1:23
	v_cmp_ge_i32_e32 vcc, s10, v199
	s_waitcnt lgkmcnt(4)
	v_and_b32_e32 v39, 0x7fffffff, v34
	s_waitcnt lgkmcnt(3)
	v_and_b32_e32 v38, 0x7fffffff, v36
	v_cndmask_b32_e32 v33, 0, v0, vcc
	v_cmp_ge_i32_e32 vcc, s2, v198
	v_xor_b32_e32 v40, -1, v36
	v_pk_add_f32 v[38:39], v[38:39], 0 neg_lo:[1,1] neg_hi:[1,1]
	v_cndmask_b32_e32 v20, 0, v20, vcc
	v_cmp_gt_i32_e32 vcc, 0, v36
	v_xor_b32_e32 v0, -1, v34
	v_and_b32_e32 v41, 0x7fffffff, v35
	v_cndmask_b32_e32 v36, v38, v40, vcc
	v_cmp_gt_i32_e32 vcc, 0, v34
	v_and_b32_e32 v40, 0x7fffffff, v37
	v_pk_add_f32 v[40:41], v[40:41], 0 neg_lo:[1,1] neg_hi:[1,1]
	v_cndmask_b32_e32 v0, v39, v0, vcc
	v_cmp_ge_i32_e32 vcc, s10, v197
	ds_read2st64_b32 v[50:51], v250 offset0:50 offset1:51
	ds_read2st64_b32 v[52:53], v250 offset0:52 offset1:53
	ds_read2st64_b32 v[54:55], v250 offset0:54 offset1:55
	v_cndmask_b32_e32 v39, 0, v0, vcc
	v_cmp_ge_i32_e32 vcc, s2, v200
	v_xor_b32_e32 v0, -1, v35
	s_waitcnt lgkmcnt(2)
	v_xor_b32_e32 v38, -1, v50
	v_cndmask_b32_e32 v34, 0, v36, vcc
	v_xor_b32_e32 v36, -1, v37
	v_cmp_gt_i32_e32 vcc, 0, v37
	v_and_b32_e32 v37, 0x7fffffff, v44
	v_and_b32_e32 v57, 0x7fffffff, v45
	v_cndmask_b32_e32 v36, v40, v36, vcc
	v_cmp_gt_i32_e32 vcc, 0, v35
	v_and_b32_e32 v56, 0x7fffffff, v51
	v_pk_add_f32 v[56:57], v[56:57], 0 neg_lo:[1,1] neg_hi:[1,1]
	v_cndmask_b32_e32 v0, v41, v0, vcc
	v_cmp_ge_i32_e32 vcc, s10, v195
	s_waitcnt lgkmcnt(1)
	v_xor_b32_e32 v40, -1, v52
	v_xor_b32_e32 v42, -1, v53
	v_cndmask_b32_e32 v41, 0, v0, vcc
	v_cmp_ge_i32_e32 vcc, s2, v202
	v_xor_b32_e32 v0, -1, v44
	s_nop 0
	v_cndmask_b32_e32 v35, 0, v36, vcc
	v_and_b32_e32 v36, 0x7fffffff, v50
	v_pk_add_f32 v[36:37], v[36:37], 0 neg_lo:[1,1] neg_hi:[1,1]
	v_cmp_gt_i32_e32 vcc, 0, v50
	v_and_b32_e32 v50, 0x7fffffff, v53
	s_nop 0
	v_cndmask_b32_e32 v36, v36, v38, vcc
	v_cmp_gt_i32_e32 vcc, 0, v44
	v_and_b32_e32 v44, 0x7fffffff, v52
	v_xor_b32_e32 v38, -1, v46
	v_cndmask_b32_e32 v0, v37, v0, vcc
	v_cmp_ge_i32_e32 vcc, s10, v193
	v_xor_b32_e32 v37, -1, v51
	s_nop 0
	v_cndmask_b32_e32 v43, 0, v0, vcc
	v_cmp_ge_i32_e32 vcc, s2, v204
	v_xor_b32_e32 v0, -1, v45
	s_nop 0
	v_cndmask_b32_e32 v36, 0, v36, vcc
	v_cmp_gt_i32_e32 vcc, 0, v51
	v_and_b32_e32 v51, 0x7fffffff, v47
	v_pk_add_f32 v[50:51], v[50:51], 0 neg_lo:[1,1] neg_hi:[1,1]
	v_cndmask_b32_e32 v37, v56, v37, vcc
	v_cmp_gt_i32_e32 vcc, 0, v45
	v_and_b32_e32 v45, 0x7fffffff, v46
	v_pk_add_f32 v[44:45], v[44:45], 0 neg_lo:[1,1] neg_hi:[1,1]
	v_cndmask_b32_e32 v0, v57, v0, vcc
	v_cmp_ge_i32_e32 vcc, s10, v191
	s_nop 1
	v_cndmask_b32_e32 v0, 0, v0, vcc
	v_cmp_ge_i32_e32 vcc, s2, v206
	s_nop 1
	v_cndmask_b32_e32 v37, 0, v37, vcc
	v_cmp_gt_i32_e32 vcc, 0, v52
	s_nop 1
	v_cndmask_b32_e32 v40, v44, v40, vcc
	v_cmp_gt_i32_e32 vcc, 0, v46
	s_waitcnt lgkmcnt(0)
	v_xor_b32_e32 v44, -1, v54
	v_cndmask_b32_e32 v38, v45, v38, vcc
	v_cmp_ge_i32_e32 vcc, s10, v189
	s_nop 1
	v_cndmask_b32_e32 v45, 0, v38, vcc
	v_cmp_ge_i32_e32 vcc, s2, v208
	s_nop 1
	v_cndmask_b32_e32 v38, 0, v40, vcc
	v_cmp_gt_i32_e32 vcc, 0, v53
	v_xor_b32_e32 v40, -1, v47
	s_nop 0
	v_cndmask_b32_e32 v42, v50, v42, vcc
	v_cmp_gt_i32_e32 vcc, 0, v47
	v_and_b32_e32 v50, 0x7fffffff, v54
	s_nop 0
	v_cndmask_b32_e32 v40, v51, v40, vcc
	v_cmp_ge_i32_e32 vcc, s10, v187
	v_and_b32_e32 v51, 0x7fffffff, v48
	v_pk_add_f32 v[50:51], v[50:51], 0 neg_lo:[1,1] neg_hi:[1,1]
	v_cndmask_b32_e32 v46, 0, v40, vcc
	v_cmp_ge_i32_e32 vcc, s2, v210
	s_nop 1
	v_cndmask_b32_e32 v40, 0, v42, vcc
	v_cmp_gt_i32_e32 vcc, 0, v54
	v_xor_b32_e32 v42, -1, v48
	s_nop 0
	v_cndmask_b32_e32 v44, v50, v44, vcc
	v_cmp_gt_i32_e32 vcc, 0, v48
	v_and_b32_e32 v50, 0x7fffffff, v55
	v_xor_b32_e32 v48, -1, v55
	v_cndmask_b32_e32 v42, v51, v42, vcc
	v_cmp_ge_i32_e32 vcc, s10, v185
	v_and_b32_e32 v51, 0x7fffffff, v49
	v_pk_add_f32 v[50:51], v[50:51], 0 neg_lo:[1,1] neg_hi:[1,1]
	v_cndmask_b32_e32 v47, 0, v42, vcc
	v_cmp_ge_i32_e32 vcc, s2, v212
	s_nop 1
	v_cndmask_b32_e32 v42, 0, v44, vcc
	v_cmp_gt_i32_e32 vcc, 0, v55
	v_xor_b32_e32 v44, -1, v49
	s_nop 0
	v_cndmask_b32_e32 v50, v50, v48, vcc
	v_cmp_gt_i32_e32 vcc, 0, v49
	s_nop 1
	v_cndmask_b32_e32 v44, v51, v44, vcc
	v_cmp_ge_i32_e32 vcc, s10, v183
	s_nop 1
	v_cndmask_b32_e32 v48, 0, v44, vcc
	v_cmp_ge_i32_e32 vcc, s2, v214
	s_nop 1
	v_cndmask_b32_e32 v44, 0, v50, vcc
	ds_read2st64_b32 v[50:51], v250 offset0:24 offset1:25
	ds_read2st64_b32 v[52:53], v250 offset0:56 offset1:57
	ds_read2st64_b32 v[56:57], v250 offset0:26 offset1:27
	ds_read2st64_b32 v[60:61], v250 offset0:28 offset1:29
	ds_read2st64_b32 v[64:65], v250 offset0:30 offset1:31
	s_waitcnt lgkmcnt(4)
	v_and_b32_e32 v55, 0x7fffffff, v50
	s_waitcnt lgkmcnt(3)
	v_and_b32_e32 v54, 0x7fffffff, v52
	s_waitcnt vmcnt(0)
	v_xor_b32_e32 v68, -1, v52
	v_pk_add_f32 v[54:55], v[54:55], 0 neg_lo:[1,1] neg_hi:[1,1]
	v_cmp_gt_i32_e32 vcc, 0, v52
	v_xor_b32_e32 v49, -1, v50
	ds_read2st64_b32 v[58:59], v250 offset0:58 offset1:59
	ds_read2st64_b32 v[62:63], v250 offset0:60 offset1:61
	ds_read2st64_b32 v[66:67], v250 offset0:62 offset1:63
	v_cndmask_b32_e32 v54, v54, v68, vcc
	v_cmp_gt_i32_e32 vcc, 0, v50
	v_xor_b32_e32 v68, -1, v53
	v_xor_b32_e32 v50, -1, v51
	v_cndmask_b32_e32 v49, v55, v49, vcc
	v_cmp_ge_i32_e32 vcc, s10, v181
	v_and_b32_e32 v55, 0x7fffffff, v51
	s_waitcnt lgkmcnt(5)
	v_and_b32_e32 v69, 0x7fffffff, v56
	v_cndmask_b32_e32 v52, 0, v49, vcc
	v_cmp_ge_i32_e32 vcc, s2, v216
	s_nop 1
	v_cndmask_b32_e32 v49, 0, v54, vcc
	v_and_b32_e32 v54, 0x7fffffff, v53
	v_pk_add_f32 v[54:55], v[54:55], 0 neg_lo:[1,1] neg_hi:[1,1]
	v_cmp_gt_i32_e32 vcc, 0, v53
	s_nop 1
	v_cndmask_b32_e32 v53, v54, v68, vcc
	v_cmp_gt_i32_e32 vcc, 0, v51
	s_waitcnt lgkmcnt(2)
	v_and_b32_e32 v68, 0x7fffffff, v58
	v_pk_add_f32 v[68:69], v[68:69], 0 neg_lo:[1,1] neg_hi:[1,1]
	v_cndmask_b32_e32 v50, v55, v50, vcc
	v_cmp_ge_i32_e32 vcc, s10, v179
	v_xor_b32_e32 v51, -1, v56
	v_xor_b32_e32 v55, -1, v59
	v_cndmask_b32_e32 v54, 0, v50, vcc
	v_cmp_ge_i32_e32 vcc, s2, v218
	s_nop 1
	v_cndmask_b32_e32 v50, 0, v53, vcc
	v_xor_b32_e32 v53, -1, v58
	v_cmp_gt_i32_e32 vcc, 0, v58
	s_nop 1
	v_cndmask_b32_e32 v53, v68, v53, vcc
	v_cmp_gt_i32_e32 vcc, 0, v56
	v_and_b32_e32 v68, 0x7fffffff, v59
	s_nop 0
	v_cndmask_b32_e32 v51, v69, v51, vcc
	v_cmp_ge_i32_e32 vcc, s10, v173
	v_and_b32_e32 v69, 0x7fffffff, v57
	v_pk_add_f32 v[68:69], v[68:69], 0 neg_lo:[1,1] neg_hi:[1,1]
	v_cndmask_b32_e32 v56, 0, v51, vcc
	v_cmp_ge_i32_e32 vcc, s2, v220
	s_nop 1
	v_cndmask_b32_e32 v51, 0, v53, vcc
	v_cmp_gt_i32_e32 vcc, 0, v59
	v_xor_b32_e32 v53, -1, v57
	s_nop 0
	v_cndmask_b32_e32 v55, v68, v55, vcc
	v_cmp_gt_i32_e32 vcc, 0, v57
	s_waitcnt lgkmcnt(1)
	v_and_b32_e32 v68, 0x7fffffff, v62
	v_xor_b32_e32 v57, -1, v62
	v_cndmask_b32_e32 v53, v69, v53, vcc
	v_cmp_ge_i32_e32 vcc, s10, v171
	v_and_b32_e32 v69, 0x7fffffff, v60
	v_pk_add_f32 v[68:69], v[68:69], 0 neg_lo:[1,1] neg_hi:[1,1]
	v_cndmask_b32_e32 v58, 0, v53, vcc
	v_cmp_ge_i32_e32 vcc, s2, v222
	s_nop 1
	v_cndmask_b32_e32 v53, 0, v55, vcc
	v_cmp_gt_i32_e32 vcc, 0, v62
	v_xor_b32_e32 v55, -1, v60
	s_waitcnt lgkmcnt(0)
	v_and_b32_e32 v62, 0x7fffffff, v66
	v_cndmask_b32_e32 v57, v68, v57, vcc
	v_cmp_gt_i32_e32 vcc, 0, v60
	v_and_b32_e32 v68, 0x7fffffff, v63
	v_xor_b32_e32 v60, -1, v63
	v_cndmask_b32_e32 v55, v69, v55, vcc
	v_cmp_ge_i32_e32 vcc, s10, v169
	v_and_b32_e32 v69, 0x7fffffff, v61
	v_pk_add_f32 v[68:69], v[68:69], 0 neg_lo:[1,1] neg_hi:[1,1]
	v_cndmask_b32_e32 v59, 0, v55, vcc
	v_cmp_ge_i32_e32 vcc, s2, v224
	s_nop 1
	v_cndmask_b32_e32 v55, 0, v57, vcc
	v_cmp_gt_i32_e32 vcc, 0, v63
	v_xor_b32_e32 v57, -1, v61
	v_and_b32_e32 v63, 0x7fffffff, v64
	v_cndmask_b32_e32 v60, v68, v60, vcc
	v_cmp_gt_i32_e32 vcc, 0, v61
	v_xor_b32_e32 v68, -1, v66
	v_pk_add_f32 v[62:63], v[62:63], 0 neg_lo:[1,1] neg_hi:[1,1]
	v_cndmask_b32_e32 v57, v69, v57, vcc
	v_cmp_ge_i32_e32 vcc, s10, v167
	v_and_b32_e32 v69, 0x7fffffff, v65
	s_nop 0
	v_cndmask_b32_e32 v61, 0, v57, vcc
	v_cmp_ge_i32_e32 vcc, s2, v226
	s_nop 1
	v_cndmask_b32_e32 v57, 0, v60, vcc
	v_cmp_gt_i32_e32 vcc, 0, v66
	v_xor_b32_e32 v60, -1, v64
	s_nop 0
	v_cndmask_b32_e32 v62, v62, v68, vcc
	v_cmp_gt_i32_e32 vcc, 0, v64
	v_and_b32_e32 v68, 0x7fffffff, v67
	v_xor_b32_e32 v64, -1, v67
	v_cndmask_b32_e32 v60, v63, v60, vcc
	v_cmp_ge_i32_e32 vcc, s10, v165
	v_pk_add_f32 v[68:69], v[68:69], 0 neg_lo:[1,1] neg_hi:[1,1]
	s_nop 0
	v_cndmask_b32_e32 v63, 0, v60, vcc
	v_cmp_ge_i32_e32 vcc, s2, v228
	s_nop 1
	v_cndmask_b32_e32 v60, 0, v62, vcc
	v_cmp_gt_i32_e32 vcc, 0, v67
	v_xor_b32_e32 v62, -1, v65
	s_nop 0
	v_cndmask_b32_e32 v66, v68, v64, vcc
	v_cmp_gt_i32_e32 vcc, 0, v65
	s_nop 1
	v_cndmask_b32_e32 v62, v69, v62, vcc
	v_cmp_ge_i32_e32 vcc, s10, v163
	s_nop 1
	v_cndmask_b32_e32 v64, 0, v62, vcc
	v_cmp_ge_i32_e32 vcc, s2, v230
	s_nop 1
	v_cndmask_b32_e32 v62, 0, v66, vcc
	s_cbranch_scc0 .LBB0_133
	s_cmpk_gt_u32 s10, 0x1ff
	s_cselect_b64 s[0:1], -1, 0
	s_cmpk_gt_u32 s10, 0x3ff
	s_cselect_b64 s[8:9], -1, 0
	s_mov_b32 s6, 0
	s_cmpk_gt_u32 s10, 0x5ff
	s_mov_b32 s24, 31
	s_mov_b32 s98, 0
	s_mov_b32 s99, 0
	s_cselect_b64 s[10:11], -1, 0
	s_mov_b32 s7, s6
	s_branch .LBB0_126
.LBB0_125:
	s_cmpk_gt_u32 s26, 0xff
	s_cselect_b32 s6, s12, s6
	s_cmpk_gt_u32 s25, 0xff
	s_cselect_b32 s7, s13, s7
	s_cmpk_eq_u32 s26, 0x100
	s_cselect_b32 s98, 1, s98
	s_cmpk_eq_u32 s25, 0x100
	s_cselect_b32 s99, 1, s99
	s_and_b32 s100, s98, s99
	s_cmp_lg_u32 s100, 0
	s_cbranch_scc1 .LBB0_132
	s_add_i32 s24, s24, -1
	s_cmp_eq_u32 s24, -1
	s_cbranch_scc1 .LBB0_132
